# 6c GEMM calls start their LDS ring at stage 1 and the next call's first two k-tiles are loaded by LDS-DMA during the current call's epilogue (cross-call prefetch)
# baseline (speedup 1.0000x reference)
; DI int otid() { int t = (int)__builtin_amdgcn_workitem_id_x(); asm volatile("" : "+v"(t)); return t; }
; #define RAW_BARRIER() do { asm volatile("s_waitcnt lgkmcnt(0)" ::: "memory"); __builtin_amdgcn_s_barrier(); } while (0)
; template <int WM, int MI, int NJ, typename AT>
; DI void gemm2(f32x4 (&acc)[MI][NJ], const AT* A, int lda, const bf16* Bt, int ldb, int K, bf16* lds) {
;   using C = G2<WM, MI, NJ>;
;   constexpr int BM = C::BM, BN = C::BN, WN = C::WN;
;   constexpr int CA = BM / 64, CB = BN / 64, NL = CA + CB;
;   static_assert(NL == 6 || NL == 4, "wait_vm covers 4 and 6");
;   const int tid = otid(), lane = tid & 63, wave = tid >> 6;
;   const int wm = wave / WN, wn = wave % WN;
;   const int fr = lane & 15, quad = lane >> 4;
;   const int nk = K >> 6;
;   const int lrow = wave * 8 + (lane >> 3), lslot = lane & 7;
;   const bf16* aptr[CA]; const bf16* bptr[CB];
; #pragma unroll
;   for (int j = 0; j < CA; ++j) { const int row = j * 64 + lrow; aptr[j] = (const bf16*)A + (size_t)row * lda + ((lslot ^ ((row >> 1) & 7)) << 3); }
; #pragma unroll
;   for (int j = 0; j < CB; ++j) { const int row = j * 64 + lrow; bptr[j] = Bt + (size_t)row * ldb + ((lslot ^ ((row >> 1) & 7)) << 3); }
;     ...
;   int aoff[MI], boff[NJ];
; #pragma unroll
;   for (int i = 0; i < MI; ++i) { const int row = wm * 16 * MI + i * 16 + fr; aoff[i] = row * 64 + ((quad ^ ((row >> 1) & 7)) << 3); }
; #pragma unroll
;   for (int j = 0; j < NJ; ++j) { const int row = wn * 16 * NJ + j * 16 + fr; boff[j] = BM * 64 + row * 64 + ((quad ^ ((row >> 1) & 7)) << 3); }
;   RAW_BARRIER();
;   G3_ISSUE(0, 0)
;   if (nk > 1) G3_ISSUE(1, 1)
;   int st = 0;
; DI void phase_tail(const Ctx& c) {
;     ...
;       f32x4 acc[4][4]; acc2_zero<4, 4>(acc);
;       gemm2<2, 4, 4, bf16>(acc, MERGED + (size_t)m0 * 1024, 1024, W + EO_WGU + (size_t)nt * 256 * DM, DM, DM, lds);
.LBB0_854:
	v_mov_b32_e32 v22, v186
	s_cmp_eq_u32 s10, 0
	s_cselect_b64 vcc, -1, 0
	s_lshl_b32 s11, s10, 19
	v_ashrrev_i32_e32 v23, 6, v22
	v_lshrrev_b32_e32 v0, 30, v23
	v_add_u32_e32 v0, v23, v0
	v_ashrrev_i32_e32 v24, 2, v0
	v_mul_i32_i24_e32 v0, 4, v24
	v_sub_u32_e32 v25, v23, v0
	v_bfe_u32 v0, v22, 3, 3
	v_lshl_or_b32 v2, v23, 3, v0
	v_lshrrev_b32_e32 v27, 1, v2
	v_xor_b32_e32 v0, v27, v22
	v_lshlrev_b32_e32 v0, 4, v0
	v_lshlrev_b32_e32 v23, 10, v23
	v_and_b32_e32 v0, 0x70, v0
	v_ashrrev_i32_e32 v3, 31, v2
	v_add_u32_e32 v10, 64, v2
	v_add_u32_e32 v85, 0x50, v23
	s_add_u32 s12, s55, s11
	v_lshl_add_u64 v[4:5], s[20:21], 0, v[0:1]
	v_lshlrev_b64 v[6:7], 11, v[2:3]
	v_ashrrev_i32_e32 v11, 31, v10
	v_readfirstlane_b32 s11, v85
	v_add_u32_e32 v29, 0x2000, v85
	s_addc_u32 s13, s90, 0
	v_lshl_add_u64 v[8:9], v[4:5], 0, v[6:7]
	v_lshlrev_b64 v[10:11], 11, v[10:11]
	s_add_i32 s11, s11, 0xc000
	s_mov_b32 m0, s11
	v_readfirstlane_b32 s11, v29
	v_add_u32_e32 v29, 0x4000, v85
	v_lshl_add_u64 v[4:5], v[4:5], 0, v[10:11]
	v_lshl_add_u64 v[12:13], s[12:13], 0, v[0:1]
	v_add_u32_e32 v18, 0x80, v2
	s_waitcnt lgkmcnt(0)
	s_barrier
	s_mov_b64 exec, vcc
	global_load_lds_dwordx4 v[8:9], off
	s_mov_b64 exec, -1
	s_add_i32 s11, s11, 0xc000
	s_mov_b32 m0, s11
	v_readfirstlane_b32 s11, v29
	v_add_u32_e32 v29, 0x6000, v85
	v_lshl_add_u64 v[14:15], v[12:13], 0, v[6:7]
	v_ashrrev_i32_e32 v19, 31, v18
	v_add_u32_e32 v2, 0xc0, v2
	s_mov_b64 exec, vcc
	global_load_lds_dwordx4 v[4:5], off
	s_mov_b64 exec, -1
	s_add_i32 s11, s11, 0xc000
	s_mov_b32 m0, s11
	v_readfirstlane_b32 s11, v29
	v_add_u32_e32 v29, 0x8000, v85
	v_lshl_add_u64 v[16:17], v[12:13], 0, v[10:11]
	v_lshlrev_b64 v[18:19], 11, v[18:19]
	v_ashrrev_i32_e32 v3, 31, v2
	s_mov_b64 exec, vcc
	global_load_lds_dwordx4 v[14:15], off
	s_mov_b64 exec, -1
	s_add_i32 s11, s11, 0xc000
	s_mov_b32 m0, s11
	v_readfirstlane_b32 s11, v29
	v_add_u32_e32 v29, 0xa000, v85
	v_lshl_add_u64 v[20:21], v[12:13], 0, v[18:19]
	v_lshlrev_b64 v[2:3], 11, v[2:3]
	s_mov_b64 exec, vcc
	global_load_lds_dwordx4 v[16:17], off
	s_mov_b64 exec, -1
	s_add_i32 s11, s11, 0xc000
	s_mov_b32 m0, s11
	v_readfirstlane_b32 s11, v29
	v_add_u32_e32 v29, 0xc000, v85
	v_lshl_add_u64 v[12:13], v[12:13], 0, v[2:3]
	s_mov_b64 exec, vcc
	global_load_lds_dwordx4 v[20:21], off
	s_mov_b64 exec, -1
	s_add_i32 s11, s11, 0xc000
	s_mov_b32 m0, s11
	s_mov_b64 s[12:13], 0x80
	v_readfirstlane_b32 s11, v29
	s_mov_b64 exec, vcc
	global_load_lds_dwordx4 v[12:13], off
	s_mov_b64 exec, -1
	v_lshl_add_u64 v[8:9], v[8:9], 0, s[12:13]
	s_add_i32 s11, s11, 0xc000
	s_mov_b32 m0, s11
	v_lshl_add_u64 v[4:5], v[4:5], 0, s[12:13]
	s_mov_b64 exec, vcc
	global_load_lds_dwordx4 v[8:9], off
	s_mov_b64 exec, -1
	v_add_u32_e32 v8, 0xe000, v85
	v_bfe_u32 v26, v22, 4, 2
	v_readfirstlane_b32 s11, v8
	v_add_u32_e32 v8, s17, v23
	s_add_i32 s11, s11, 0xc000
	s_mov_b32 m0, s11
	v_readfirstlane_b32 s11, v8
	v_add_u32_e32 v9, 0x2000, v8
	s_mov_b64 exec, vcc
	global_load_lds_dwordx4 v[4:5], off
	s_mov_b64 exec, -1
	v_lshl_add_u64 v[4:5], v[14:15], 0, s[12:13]
	s_add_i32 s11, s11, 0xc000
	s_mov_b32 m0, s11
	v_readfirstlane_b32 s11, v9
	v_add_u32_e32 v9, 0x4000, v8
	s_mov_b64 exec, vcc
	global_load_lds_dwordx4 v[4:5], off
	s_mov_b64 exec, -1
	v_lshl_add_u64 v[4:5], v[16:17], 0, s[12:13]
	s_add_i32 s11, s11, 0xc000
	s_mov_b32 m0, s11
	v_readfirstlane_b32 s11, v9
	v_add_u32_e32 v8, 0x6000, v8
	s_mov_b64 exec, vcc
	global_load_lds_dwordx4 v[4:5], off
	s_mov_b64 exec, -1
	v_lshl_add_u64 v[4:5], v[20:21], 0, s[12:13]
	s_add_i32 s11, s11, 0xc000
	s_mov_b32 m0, s11
	v_readfirstlane_b32 s11, v8
	s_mov_b64 exec, vcc
	global_load_lds_dwordx4 v[4:5], off
	s_mov_b64 exec, -1
	v_lshl_add_u64 v[4:5], v[12:13], 0, s[12:13]
	s_add_i32 s11, s11, 0xc000
	s_mov_b32 m0, s11
	v_lshrrev_b32_e32 v0, 1, v22
	s_mov_b64 exec, vcc
	global_load_lds_dwordx4 v[4:5], off
	s_mov_b64 exec, -1
	v_bitop3_b32 v0, v26, v0, 7 bitop3:0x78
	v_lshlrev_b32_e32 v26, 6, v22
	v_bitop3_b32 v4, v27, 7, v22 bitop3:0x48
	v_lshlrev_b32_e32 v0, 3, v0
	v_and_b32_e32 v26, 0x3c0, v26
	v_lshlrev_b32_e32 v25, 12, v25
	v_lshlrev_b32_e32 v4, 4, v4
	v_or3_b32 v83, v25, v26, v0
	v_or_b32_e32 v2, v2, v4
	v_lshl_or_b32 v24, v24, 12, v26
	v_add_u32_e32 v82, 0x2000, v83
	v_add_u32_e32 v25, 0x2400, v83
	v_add_u32_e32 v26, 0x2800, v83
	v_add_u32_e32 v28, 0x2c00, v83
	v_lshl_add_u64 v[66:67], s[0:1], 0, v[2:3]
	v_or_b32_e32 v18, v18, v4
	v_or_b32_e32 v10, v10, v4
	v_or_b32_e32 v6, v6, v4
	v_mov_b32_e32 v2, 0
	v_or_b32_e32 v84, v24, v0
	v_bitop3_b32 v81, v24, 32, v0 bitop3:0x36
	v_xor_b32_e32 v80, 32, v82
	v_xor_b32_e32 v79, 32, v25
	v_xor_b32_e32 v78, 32, v26
	v_xor_b32_e32 v0, 32, v28
	v_lshl_add_u64 v[68:69], s[0:1], 0, v[18:19]
	v_lshl_add_u64 v[70:71], s[0:1], 0, v[10:11]
	v_lshl_add_u64 v[72:73], s[0:1], 0, v[6:7]
	v_lshl_add_u64 v[74:75], s[22:23], 0, v[10:11]
	v_lshl_add_u64 v[76:77], s[22:23], 0, v[6:7]
	s_mov_b64 s[28:29], 0
	s_mov_b32 s11, 1
	v_mov_b32_e32 v3, v2
	v_mov_b32_e32 v4, v2
	v_mov_b32_e32 v5, v2
	v_mov_b32_e32 v6, v2
	v_mov_b32_e32 v7, v2
	v_mov_b32_e32 v8, v2
	v_mov_b32_e32 v9, v2
	v_mov_b32_e32 v10, v2
	v_mov_b32_e32 v11, v2
	v_mov_b32_e32 v12, v2
	v_mov_b32_e32 v13, v2
	v_mov_b32_e32 v14, v2
	v_mov_b32_e32 v15, v2
	v_mov_b32_e32 v16, v2
	v_mov_b32_e32 v17, v2
	v_mov_b32_e32 v18, v2
	v_mov_b32_e32 v19, v2
	v_mov_b32_e32 v20, v2
	v_mov_b32_e32 v21, v2
	v_mov_b32_e32 v22, v2
	v_mov_b32_e32 v23, v2
	v_mov_b32_e32 v24, v2
	v_mov_b32_e32 v25, v2
	v_mov_b32_e32 v26, v2
	v_mov_b32_e32 v27, v2
	v_mov_b32_e32 v28, v2
	v_mov_b32_e32 v29, v2
	v_mov_b32_e32 v30, v2
	v_mov_b32_e32 v31, v2
	v_mov_b32_e32 v32, v2
	v_mov_b32_e32 v33, v2
	v_mov_b32_e32 v34, v2
	v_mov_b32_e32 v35, v2
	v_mov_b32_e32 v36, v2
	v_mov_b32_e32 v37, v2
	v_mov_b32_e32 v38, v2
	v_mov_b32_e32 v39, v2
	v_mov_b32_e32 v40, v2
	v_mov_b32_e32 v41, v2
	v_mov_b32_e32 v42, v2
	v_mov_b32_e32 v43, v2
	v_mov_b32_e32 v44, v2
	v_mov_b32_e32 v45, v2
	v_mov_b32_e32 v46, v2
	v_mov_b32_e32 v47, v2
	v_mov_b32_e32 v48, v2
	v_mov_b32_e32 v49, v2
	v_mov_b32_e32 v50, v2
	v_mov_b32_e32 v51, v2
	v_mov_b32_e32 v52, v2
	v_mov_b32_e32 v53, v2
	v_mov_b32_e32 v54, v2
	v_mov_b32_e32 v55, v2
	v_mov_b32_e32 v56, v2
	v_mov_b32_e32 v57, v2
	v_mov_b32_e32 v58, v2
	v_mov_b32_e32 v59, v2
	v_mov_b32_e32 v60, v2
	v_mov_b32_e32 v61, v2
	v_mov_b32_e32 v62, v2
	v_mov_b32_e32 v63, v2
	v_mov_b32_e32 v64, v2
	v_mov_b32_e32 v65, v2
; #define MFMA16(a, b, c) __builtin_amdgcn_mfma_f32_16x16x32_bf16((a), (b), (c), 0, 0, 0)
; #define RAW_BARRIER() do { asm volatile("s_waitcnt lgkmcnt(0)" ::: "memory"); __builtin_amdgcn_s_barrier(); } while (0)
; template <int WM, int MI, int NJ, typename AT>
; DI void gemm2(f32x4 (&acc)[MI][NJ], const AT* A, int lda, const bf16* Bt, int ldb, int K, bf16* lds) {
;     ...
;   for (int kt = 0; kt < nk; ++kt) {
;     if (kt + 1 < nk) wait_vm<NL>(); else wait_vm<0>();
;     RAW_BARRIER();
;     if (kt + 2 < nk) { const int st2 = (st + 2 >= 3) ? st - 1 : st + 2; G3_ISSUE(kt + 2, st2) }
;     const bf16* sp = lds + st * G3_STAGE;
; #pragma unroll
;     for (int kk = 0; kk < 2; ++kk) {
;       bf16x8 a[MI], b[NJ];
; #pragma unroll
;       for (int i = 0; i < MI; ++i) a[i] = *(const bf16x8*)(sp + (aoff[i] ^ (kk << 5)));
; #pragma unroll
;       for (int j = 0; j < NJ; ++j) b[j] = *(const bf16x8*)(sp + (boff[j] ^ (kk << 5)));
; #pragma unroll
;       for (int i = 0; i < MI; ++i)
; #pragma unroll
;         for (int j = 0; j < NJ; ++j) acc[i][j] = MFMA16(a[i], b[j], acc[i][j]);
;     }
;     st = (st == 2) ? 0 : st + 1;
;   }
.LBB0_855:
	s_cmp_gt_i32 s11, 0
	s_cselect_b32 s12, -1, 2
	s_add_i32 s12, s12, s11
	s_mul_i32 s12, s12, 0xc000
	v_add_u32_e32 v88, s12, v85
	v_add_u32_e32 v89, 0x2000, v88
	v_readfirstlane_b32 s12, v88
	s_waitcnt vmcnt(6)
	v_lshl_add_u64 v[86:87], v[76:77], 0, s[28:29]
	s_mov_b32 m0, s12
	v_readfirstlane_b32 s12, v89
	v_add_u32_e32 v89, 0x4000, v88
	s_waitcnt lgkmcnt(0)
	s_barrier
	global_load_lds_dwordx4 v[86:87], off
	v_lshl_add_u64 v[86:87], v[74:75], 0, s[28:29]
	s_mov_b32 m0, s12
	v_readfirstlane_b32 s12, v89
	v_add_u32_e32 v89, 0x6000, v88
	global_load_lds_dwordx4 v[86:87], off
	v_lshl_add_u64 v[86:87], v[72:73], 0, s[28:29]
	s_mov_b32 m0, s12
	v_readfirstlane_b32 s12, v89
	v_add_u32_e32 v89, 0x8000, v88
	global_load_lds_dwordx4 v[86:87], off
	v_lshl_add_u64 v[86:87], v[70:71], 0, s[28:29]
	s_mov_b32 m0, s12
	v_readfirstlane_b32 s12, v89
	v_add_u32_e32 v88, 0xa000, v88
	global_load_lds_dwordx4 v[86:87], off
	v_lshl_add_u64 v[86:87], v[68:69], 0, s[28:29]
	s_mov_b32 m0, s12
	v_readfirstlane_b32 s12, v88
	global_load_lds_dwordx4 v[86:87], off
	v_lshl_add_u64 v[86:87], v[66:67], 0, s[28:29]
	s_mov_b32 m0, s12
	s_mul_i32 s12, s11, 0xc000
	global_load_lds_dwordx4 v[86:87], off
	s_addk_i32 s12, 0x50
	v_lshl_add_u32 v98, v84, 1, s12
	v_lshl_add_u32 v102, v83, 1, s12
	v_lshl_add_u32 v114, v82, 1, s12
	ds_read_b128 v[86:89], v98
	ds_read_b128 v[90:93], v98 offset:2048
	ds_read_b128 v[94:97], v98 offset:4096
	ds_read_b128 v[98:101], v98 offset:6144
	ds_read_b128 v[102:105], v102 offset:16384
	ds_read_b128 v[106:109], v114 offset:2048
	ds_read_b128 v[110:113], v114 offset:4096
	ds_read_b128 v[114:117], v114 offset:6144
	s_waitcnt lgkmcnt(0)
	v_mfma_f32_16x16x32_bf16 v[62:65], v[86:89], v[102:105], v[62:65]
	v_mfma_f32_16x16x32_bf16 v[58:61], v[86:89], v[106:109], v[58:61]
	v_mfma_f32_16x16x32_bf16 v[54:57], v[86:89], v[110:113], v[54:57]
	v_mfma_f32_16x16x32_bf16 v[50:53], v[86:89], v[114:117], v[50:53]
	v_mfma_f32_16x16x32_bf16 v[46:49], v[90:93], v[102:105], v[46:49]
	v_mfma_f32_16x16x32_bf16 v[42:45], v[90:93], v[106:109], v[42:45]
	v_mfma_f32_16x16x32_bf16 v[38:41], v[90:93], v[110:113], v[38:41]
	v_mfma_f32_16x16x32_bf16 v[34:37], v[90:93], v[114:117], v[34:37]
	v_mfma_f32_16x16x32_bf16 v[30:33], v[94:97], v[102:105], v[30:33]
	v_mfma_f32_16x16x32_bf16 v[26:29], v[94:97], v[106:109], v[26:29]
	v_mfma_f32_16x16x32_bf16 v[22:25], v[94:97], v[110:113], v[22:25]
	v_mfma_f32_16x16x32_bf16 v[18:21], v[94:97], v[114:117], v[18:21]
	v_mfma_f32_16x16x32_bf16 v[14:17], v[98:101], v[102:105], v[14:17]
	v_lshl_add_u32 v102, v80, 1, s12
	v_mfma_f32_16x16x32_bf16 v[10:13], v[98:101], v[106:109], v[10:13]
	v_lshl_add_u32 v106, v79, 1, s12
	v_mfma_f32_16x16x32_bf16 v[6:9], v[98:101], v[110:113], v[6:9]
	v_lshl_add_u32 v110, v78, 1, s12
	v_mfma_f32_16x16x32_bf16 v[2:5], v[98:101], v[114:117], v[2:5]
	v_lshl_add_u32 v98, v81, 1, s12
	v_lshl_add_u32 v114, v0, 1, s12
	ds_read_b128 v[86:89], v98
	ds_read_b128 v[90:93], v98 offset:2048
	ds_read_b128 v[94:97], v98 offset:4096
	ds_read_b128 v[98:101], v98 offset:6144
	ds_read_b128 v[102:105], v102
	ds_read_b128 v[106:109], v106
	ds_read_b128 v[110:113], v110
	ds_read_b128 v[114:117], v114
	s_add_i32 s12, s11, 1
	s_waitcnt lgkmcnt(0)
	v_mfma_f32_16x16x32_bf16 v[62:65], v[86:89], v[102:105], v[62:65]
	s_cmp_lg_u32 s11, 2
	s_cselect_b32 s11, s12, 0
	s_add_u32 s28, s28, 0x80
	v_mfma_f32_16x16x32_bf16 v[58:61], v[86:89], v[106:109], v[58:61]
	s_addc_u32 s29, s29, 0
	s_cmpk_lg_i32 s28, 0x700
	v_mfma_f32_16x16x32_bf16 v[54:57], v[86:89], v[110:113], v[54:57]
	v_mfma_f32_16x16x32_bf16 v[50:53], v[86:89], v[114:117], v[50:53]
	v_mfma_f32_16x16x32_bf16 v[46:49], v[90:93], v[102:105], v[46:49]
	v_mfma_f32_16x16x32_bf16 v[42:45], v[90:93], v[106:109], v[42:45]
	v_mfma_f32_16x16x32_bf16 v[38:41], v[90:93], v[110:113], v[38:41]
	v_mfma_f32_16x16x32_bf16 v[34:37], v[90:93], v[114:117], v[34:37]
	v_mfma_f32_16x16x32_bf16 v[30:33], v[94:97], v[102:105], v[30:33]
	v_mfma_f32_16x16x32_bf16 v[26:29], v[94:97], v[106:109], v[26:29]
	v_mfma_f32_16x16x32_bf16 v[22:25], v[94:97], v[110:113], v[22:25]
	v_mfma_f32_16x16x32_bf16 v[18:21], v[94:97], v[114:117], v[18:21]
	v_mfma_f32_16x16x32_bf16 v[14:17], v[98:101], v[102:105], v[14:17]
	v_mfma_f32_16x16x32_bf16 v[10:13], v[98:101], v[106:109], v[10:13]
	v_mfma_f32_16x16x32_bf16 v[6:9], v[98:101], v[110:113], v[6:9]
	v_mfma_f32_16x16x32_bf16 v[2:5], v[98:101], v[114:117], v[2:5]
	s_cbranch_scc1 .LBB0_855
	s_mul_i32 s11, s11, 0xc000
	s_addk_i32 s11, 0x50
	v_lshlrev_b32_e32 v104, 1, v84
	v_lshlrev_b32_e32 v105, 1, v83
	v_lshlrev_b32_e32 v106, 1, v82
	s_waitcnt vmcnt(6)
	v_add_u32_e32 v84, s11, v104
	v_add_u32_e32 v83, s11, v105
	v_add_u32_e32 v82, s11, v106
	s_waitcnt lgkmcnt(0)
	s_barrier
; #define MFMA16(a, b, c) __builtin_amdgcn_mfma_f32_16x16x32_bf16((a), (b), (c), 0, 0, 0)
; #define RAW_BARRIER() do { asm volatile("s_waitcnt lgkmcnt(0)" ::: "memory"); __builtin_amdgcn_s_barrier(); } while (0)
; template <int WM, int MI, int NJ, typename AT>
; DI void gemm2(f32x4 (&acc)[MI][NJ], const AT* A, int lda, const bf16* Bt, int ldb, int K, bf16* lds) {
;     ...
;   for (int kt = 0; kt < nk; ++kt) {
;     if (kt + 1 < nk) wait_vm<NL>(); else wait_vm<0>();
;     RAW_BARRIER();
;     if (kt + 2 < nk) { const int st2 = (st + 2 >= 3) ? st - 1 : st + 2; G3_ISSUE(kt + 2, st2) }
;     const bf16* sp = lds + st * G3_STAGE;
; #pragma unroll
;     for (int kk = 0; kk < 2; ++kk) {
;       bf16x8 a[MI], b[NJ];
; #pragma unroll
;       for (int i = 0; i < MI; ++i) a[i] = *(const bf16x8*)(sp + (aoff[i] ^ (kk << 5)));
; #pragma unroll
;       for (int j = 0; j < NJ; ++j) b[j] = *(const bf16x8*)(sp + (boff[j] ^ (kk << 5)));
; #pragma unroll
;       for (int i = 0; i < MI; ++i)
; #pragma unroll
;         for (int j = 0; j < NJ; ++j) acc[i][j] = MFMA16(a[i], b[j], acc[i][j]);
;     }
;     st = (st == 2) ? 0 : st + 1;
;   }
	ds_read_b128 v[66:69], v84
	ds_read_b128 v[70:73], v84 offset:2048
	ds_read_b128 v[74:77], v84 offset:4096
	ds_read_b128 v[84:87], v84 offset:6144
	ds_read_b128 v[88:91], v83 offset:16384
	ds_read_b128 v[92:95], v82 offset:2048
	ds_read_b128 v[96:99], v82 offset:4096
	ds_read_b128 v[100:103], v82 offset:6144
	s_waitcnt lgkmcnt(0)
	v_mfma_f32_16x16x32_bf16 v[50:53], v[66:69], v[100:103], v[50:53]
	v_lshlrev_b32_e32 v107, 1, v79
	v_lshlrev_b32_e32 v108, 1, v78
	v_lshlrev_b32_e32 v0, 1, v0
	v_mfma_f32_16x16x32_bf16 v[34:37], v[70:73], v[100:103], v[34:37]
	v_add_u32_e32 v79, s11, v107
	v_add_u32_e32 v78, s11, v108
	v_mfma_f32_16x16x32_bf16 v[18:21], v[74:77], v[100:103], v[18:21]
	v_mfma_f32_16x16x32_bf16 v[2:5], v[84:87], v[100:103], v[2:5]
	v_lshlrev_b32_e32 v102, 1, v81
	v_lshlrev_b32_e32 v103, 1, v80
	v_add_u32_e32 v81, s11, v102
	v_mfma_f32_16x16x32_bf16 v[58:61], v[66:69], v[92:95], v[58:61]
	v_add_u32_e32 v80, s11, v103
	v_mfma_f32_16x16x32_bf16 v[42:45], v[70:73], v[92:95], v[42:45]
	v_mfma_f32_16x16x32_bf16 v[26:29], v[74:77], v[92:95], v[26:29]
	v_mfma_f32_16x16x32_bf16 v[10:13], v[84:87], v[92:95], v[10:13]
	v_add_u32_e32 v94, s11, v0
	v_add_u32_e32 v0, 0xc050, v0
	s_movk_i32 s11, 0x800
	v_mfma_f32_16x16x32_bf16 v[62:65], v[66:69], v[88:91], v[62:65]
	v_mfma_f32_16x16x32_bf16 v[54:57], v[66:69], v[96:99], v[54:57]
	v_mfma_f32_16x16x32_bf16 v[46:49], v[70:73], v[88:91], v[46:49]
	v_mfma_f32_16x16x32_bf16 v[38:41], v[70:73], v[96:99], v[38:41]
	v_mfma_f32_16x16x32_bf16 v[30:33], v[74:77], v[88:91], v[30:33]
	v_mfma_f32_16x16x32_bf16 v[22:25], v[74:77], v[96:99], v[22:25]
	v_mfma_f32_16x16x32_bf16 v[14:17], v[84:87], v[88:91], v[14:17]
	v_mfma_f32_16x16x32_bf16 v[6:9], v[84:87], v[96:99], v[6:9]
	ds_read_b128 v[66:69], v81
	ds_read_b128 v[70:73], v81 offset:2048
	ds_read_b128 v[74:77], v81 offset:4096
	ds_read_b128 v[82:85], v81 offset:6144
	ds_read_b128 v[86:89], v80
	ds_read_b128 v[90:93], v79
	ds_read_b128 v[78:81], v78
	ds_read_b128 v[94:97], v94
	s_waitcnt lgkmcnt(0)
	v_mfma_f32_16x16x32_bf16 v[54:57], v[66:69], v[78:81], v[54:57]
	s_waitcnt vmcnt(0)
	s_waitcnt lgkmcnt(0)
	s_barrier
	v_mfma_f32_16x16x32_bf16 v[50:53], v[66:69], v[94:97], v[50:53]
	v_mfma_f32_16x16x32_bf16 v[38:41], v[70:73], v[78:81], v[38:41]
	v_mfma_f32_16x16x32_bf16 v[34:37], v[70:73], v[94:97], v[34:37]
	v_mfma_f32_16x16x32_bf16 v[22:25], v[74:77], v[78:81], v[22:25]
	v_mfma_f32_16x16x32_bf16 v[18:21], v[74:77], v[94:97], v[18:21]
	v_mfma_f32_16x16x32_bf16 v[14:17], v[82:85], v[86:89], v[14:17]
	v_mfma_f32_16x16x32_bf16 v[10:13], v[82:85], v[90:93], v[10:13]
	v_mfma_f32_16x16x32_bf16 v[6:9], v[82:85], v[78:81], v[6:9]
	v_add_u32_e32 v78, 0xc050, v104
	v_mfma_f32_16x16x32_bf16 v[2:5], v[82:85], v[94:97], v[2:5]
	v_add_u32_e32 v82, 0xc050, v105
	v_add_u32_e32 v94, 0xc050, v106
	v_mfma_f32_16x16x32_bf16 v[62:65], v[66:69], v[86:89], v[62:65]
	v_mfma_f32_16x16x32_bf16 v[58:61], v[66:69], v[90:93], v[58:61]
	v_mfma_f32_16x16x32_bf16 v[46:49], v[70:73], v[86:89], v[46:49]
	v_mfma_f32_16x16x32_bf16 v[42:45], v[70:73], v[90:93], v[42:45]
	v_mfma_f32_16x16x32_bf16 v[30:33], v[74:77], v[86:89], v[30:33]
	v_mfma_f32_16x16x32_bf16 v[26:29], v[74:77], v[90:93], v[26:29]
	ds_read_b128 v[66:69], v78
	ds_read_b128 v[70:73], v78 offset:2048
	ds_read_b128 v[74:77], v78 offset:4096
	ds_read_b128 v[78:81], v78 offset:6144
	ds_read_b128 v[82:85], v82 offset:16384
	ds_read_b128 v[86:89], v94 offset:2048
	ds_read_b128 v[90:93], v94 offset:4096
	ds_read_b128 v[94:97], v94 offset:6144
	s_waitcnt lgkmcnt(0)
	v_mfma_f32_16x16x32_bf16 v[30:33], v[74:77], v[82:85], v[30:33]
	v_mfma_f32_16x16x32_bf16 v[98:101], v[74:77], v[86:89], v[26:29]
	v_mfma_f32_16x16x32_bf16 v[22:25], v[74:77], v[90:93], v[22:25]
	v_mfma_f32_16x16x32_bf16 v[74:77], v[74:77], v[94:97], v[18:21]
	s_nop 2
	v_add_u32_e32 v18, 0xc050, v102
	v_mfma_f32_16x16x32_bf16 v[62:65], v[66:69], v[82:85], v[62:65]
	v_mfma_f32_16x16x32_bf16 v[58:61], v[66:69], v[86:89], v[58:61]
	v_mfma_f32_16x16x32_bf16 v[54:57], v[66:69], v[90:93], v[54:57]
	v_mfma_f32_16x16x32_bf16 v[50:53], v[66:69], v[94:97], v[50:53]
	v_mfma_f32_16x16x32_bf16 v[46:49], v[70:73], v[82:85], v[46:49]
	v_mfma_f32_16x16x32_bf16 v[66:69], v[70:73], v[86:89], v[42:45]
	v_mfma_f32_16x16x32_bf16 v[38:41], v[70:73], v[90:93], v[38:41]
	v_mfma_f32_16x16x32_bf16 v[14:17], v[78:81], v[82:85], v[14:17]
	v_mfma_f32_16x16x32_bf16 v[82:85], v[78:81], v[86:89], v[10:13]
	v_mfma_f32_16x16x32_bf16 v[6:9], v[78:81], v[90:93], v[6:9]
	v_mfma_f32_16x16x32_bf16 v[78:81], v[78:81], v[94:97], v[2:5]
	s_nop 2
	ds_read_b128 v[2:5], v18
	ds_read_b128 v[10:13], v18 offset:2048
	ds_read_b128 v[86:89], v18 offset:4096
	ds_read_b128 v[90:93], v18 offset:6144
	v_add_u32_e32 v18, 0xc050, v103
	ds_read_b128 v[110:113], v0
	v_mfma_f32_16x16x32_bf16 v[70:73], v[70:73], v[94:97], v[34:37]
	ds_read_b128 v[94:97], v18
	v_add_u32_e32 v18, 0xc050, v107
	ds_read_b128 v[102:105], v18
	v_add_u32_e32 v18, 0xc050, v108
	ds_read_b128 v[106:109], v18
	s_waitcnt lgkmcnt(0)
	v_mfma_f32_16x16x32_bf16 v[42:45], v[10:13], v[94:97], v[46:49]
	s_waitcnt vmcnt(0)
	s_barrier
	s_cmp_eq_u32 s10, 21
	s_cbranch_scc1 .Lx6c_skip
; DI float siluf_(float x) { return x / (1.f + __expf(-x)); }
; #define RAW_BARRIER() do { asm volatile("s_waitcnt lgkmcnt(0)" ::: "memory"); __builtin_amdgcn_s_barrier(); } while (0)
; template <int BN_OUT> DI void ct_put(bf16* lds, int row, int col, float v) { lds[row * (BN_OUT + 8) + col] = f2bf(v); }
; template <int WM, int MI, int NJ, typename AT>
; DI void gemm2(f32x4 (&acc)[MI][NJ], const AT* A, int lda, const bf16* Bt, int ldb, int K, bf16* lds) {
;     ...
;   int aoff[MI], boff[NJ];
; #pragma unroll
;   for (int i = 0; i < MI; ++i) { const int row = wm * 16 * MI + i * 16 + fr; aoff[i] = row * 64 + ((quad ^ ((row >> 1) & 7)) << 3); }
; #pragma unroll
;   for (int j = 0; j < NJ; ++j) { const int row = wn * 16 * NJ + j * 16 + fr; boff[j] = BM * 64 + row * 64 + ((quad ^ ((row >> 1) & 7)) << 3); }
;   RAW_BARRIER();
;   G3_ISSUE(0, 0)
;   if (nk > 1) G3_ISSUE(1, 1)
; DI void phase_tail(const Ctx& c) {
;     ...
; #pragma unroll
;       for (int i = 0; i < 4; ++i)
; #pragma unroll
;         for (int r = 0; r < 4; ++r) {
;           const int row = wm * 64 + i * 16 + (lane >> 4) * 4 + r;
;           const float rs = rstd2[row];
; #pragma unroll
;           for (int pp = 0; pp < 2; ++pp) {
;             const float g = acc[i][2 * pp][r] * rs, u = acc[i][2 * pp + 1][r] * rs;
;             ct_put<128>(lds, row, (wn * 2 + pp) * 16 + (lane & 15), siluf_(g) * u);
;           }
;         }
;       ct_flush<128, 128>(lds, F + (size_t)m0 * DFF + nt * 128, DFF);
	v_lshrrev_b32_e32 v230, 6, v186
	v_bfe_u32 v231, v186, 3, 3
	v_lshl_or_b32 v230, v230, 3, v231
	v_lshrrev_b32_e32 v231, 1, v230
	v_xor_b32_e32 v231, v231, v186
	v_lshlrev_b32_e32 v231, 4, v231
	v_and_b32_e32 v231, 0x70, v231
	v_lshl_or_b32 v232, v230, 11, v231
	v_mov_b32_e32 v233, 0
	v_mov_b32_e32 v240, 0x20000
	v_mov_b32_e32 v241, 0
	v_mov_b32_e32 v250, 0x80
	v_mov_b32_e32 v251, 0
	s_add_i32 s100, s10, 1
	s_lshl_b32 s100, s100, 19
	s_add_u32 s100, s55, s100
	s_addc_u32 s101, s90, 0
	v_lshl_add_u64 v[234:235], s[20:21], 0, v[232:233]
	v_lshl_add_u64 v[236:237], v[234:235], 0, v[240:241]
	v_lshl_add_u64 v[242:243], s[100:101], 0, v[232:233]
	v_lshl_add_u64 v[244:245], v[242:243], 0, v[240:241]
	v_lshl_add_u64 v[246:247], v[244:245], 0, v[240:241]
	v_lshl_add_u64 v[248:249], v[246:247], 0, v[240:241]
	v_readfirstlane_b32 s100, v186
	s_lshr_b32 s100, s100, 6
	s_lshl_b32 s100, s100, 10
	s_add_i32 s100, s100, 0xc050
	s_add_i32 s101, s100, 0x0
	s_mov_b32 m0, s101
	s_nop 0
	global_load_lds_dwordx4 v[234:235], off
	s_add_i32 s101, s100, 0x2000
	s_mov_b32 m0, s101
	s_nop 0
	global_load_lds_dwordx4 v[236:237], off
	s_add_i32 s101, s100, 0x4000
	s_mov_b32 m0, s101
	s_nop 0
	global_load_lds_dwordx4 v[242:243], off
	s_add_i32 s101, s100, 0x6000
	s_mov_b32 m0, s101
	s_nop 0
	global_load_lds_dwordx4 v[244:245], off
	s_add_i32 s101, s100, 0x8000
	s_mov_b32 m0, s101
	s_nop 0
	global_load_lds_dwordx4 v[246:247], off
	s_add_i32 s101, s100, 0xa000
	s_mov_b32 m0, s101
	s_nop 0
	global_load_lds_dwordx4 v[248:249], off
	v_lshl_add_u64 v[234:235], v[234:235], 0, v[250:251]
	v_lshl_add_u64 v[236:237], v[236:237], 0, v[250:251]
	v_lshl_add_u64 v[242:243], v[242:243], 0, v[250:251]
	v_lshl_add_u64 v[244:245], v[244:245], 0, v[250:251]
	v_lshl_add_u64 v[246:247], v[246:247], 0, v[250:251]
	v_lshl_add_u64 v[248:249], v[248:249], 0, v[250:251]
	s_add_i32 s101, s100, 0xc000
	s_mov_b32 m0, s101
	s_nop 0
	global_load_lds_dwordx4 v[234:235], off
	s_add_i32 s101, s100, 0xe000
	s_mov_b32 m0, s101
	s_nop 0
	global_load_lds_dwordx4 v[236:237], off
	s_add_i32 s101, s100, 0x10000
	s_mov_b32 m0, s101
	s_nop 0
	global_load_lds_dwordx4 v[242:243], off
	s_add_i32 s101, s100, 0x12000
	s_mov_b32 m0, s101
	s_nop 0
	global_load_lds_dwordx4 v[244:245], off
	s_add_i32 s101, s100, 0x14000
	s_mov_b32 m0, s101
	s_nop 0
	global_load_lds_dwordx4 v[246:247], off
	s_add_i32 s101, s100, 0x16000
	s_mov_b32 m0, s101
	s_nop 0
	global_load_lds_dwordx4 v[248:249], off
.Lx6c_skip:
	v_mfma_f32_16x16x32_bf16 v[46:49], v[10:13], v[102:105], v[66:69]
	s_nop 2
	ds_read_b128 v[66:69], v143
	v_mfma_f32_16x16x32_bf16 v[62:65], v[2:5], v[94:97], v[62:65]
	v_mfma_f32_16x16x32_bf16 v[34:37], v[10:13], v[106:109], v[38:41]
	v_mfma_f32_16x16x32_bf16 v[38:41], v[10:13], v[110:113], v[70:73]
	s_waitcnt lgkmcnt(0)
	s_nop 4
	v_mul_f32_e32 v0, v62, v66
	v_mul_f32_e32 v62, 0xbfb8aa3b, v0
	v_exp_f32_e32 v62, v62
	v_mfma_f32_16x16x32_bf16 v[58:61], v[2:5], v[102:105], v[58:61]
	v_add_f32_e32 v62, 1.0, v62
	v_div_scale_f32 v70, s[12:13], v62, v62, v0
	v_rcp_f32_e32 v71, v70
	v_mfma_f32_16x16x32_bf16 v[18:21], v[86:89], v[106:109], v[22:25]
	s_nop 3
	v_mul_f32_e32 v58, v58, v66
	v_fma_f32 v72, -v70, v71, 1.0
	v_fmac_f32_e32 v71, v72, v71
	v_div_scale_f32 v72, vcc, v0, v62, v0
	v_mul_f32_e32 v73, v72, v71
	v_mfma_f32_16x16x32_bf16 v[22:25], v[86:89], v[110:113], v[74:77]
	s_nop 2
	v_fma_f32 v74, -v70, v73, v72
	v_fmac_f32_e32 v73, v74, v71
	v_fma_f32 v70, -v70, v73, v72
	v_mfma_f32_16x16x32_bf16 v[54:57], v[2:5], v[106:109], v[54:57]
	v_div_fmas_f32 v70, v70, v71, v73
	v_div_fixup_f32 v0, v70, v62, v0
	v_mul_f32_e32 v0, v58, v0
	v_cvt_pk_bf16_f32 v0, v0, s0
	ds_write_b16 v144, v0
	s_nop 2
	v_mul_f32_e32 v0, v54, v66
	v_mul_f32_e32 v54, 0xbfb8aa3b, v0
	v_exp_f32_e32 v54, v54
	v_mfma_f32_16x16x32_bf16 v[50:53], v[2:5], v[110:113], v[50:53]
	v_add_f32_e32 v54, 1.0, v54
	v_div_scale_f32 v58, s[12:13], v54, v54, v0
	v_rcp_f32_e32 v62, v58
	s_nop 4
	v_mul_f32_e32 v50, v50, v66
	v_mfma_f32_16x16x32_bf16 v[26:29], v[86:89], v[94:97], v[30:33]
	v_fma_f32 v66, -v58, v62, 1.0
	v_fmac_f32_e32 v62, v66, v62
	v_div_scale_f32 v66, vcc, v0, v54, v0
	v_mul_f32_e32 v70, v66, v62
	v_fma_f32 v71, -v58, v70, v66
	v_fmac_f32_e32 v70, v71, v62
	v_fma_f32 v58, -v58, v70, v66
	v_div_fmas_f32 v58, v58, v62, v70
	v_div_fixup_f32 v0, v58, v54, v0
	v_mul_f32_e32 v0, v50, v0
	v_cvt_pk_bf16_f32 v0, v0, s0
	ds_write_b16 v144, v0 offset:32
	v_mul_f32_e32 v0, v63, v67
	v_mul_f32_e32 v54, 0xbfb8aa3b, v0
	v_exp_f32_e32 v54, v54
	v_mul_f32_e32 v50, v59, v67
	v_mfma_f32_16x16x32_bf16 v[30:33], v[86:89], v[102:105], v[98:101]
	v_add_f32_e32 v54, 1.0, v54
	v_div_scale_f32 v58, s[12:13], v54, v54, v0
	v_rcp_f32_e32 v59, v58
	v_mfma_f32_16x16x32_bf16 v[10:13], v[90:93], v[94:97], v[14:17]
	v_fma_f32 v62, -v58, v59, 1.0
	v_fmac_f32_e32 v59, v62, v59
	v_div_scale_f32 v62, vcc, v0, v54, v0
	v_mul_f32_e32 v63, v62, v59
	v_fma_f32 v66, -v58, v63, v62
	v_fmac_f32_e32 v63, v66, v59
	v_fma_f32 v58, -v58, v63, v62
	v_div_fmas_f32 v58, v58, v59, v63
	v_div_fixup_f32 v0, v58, v54, v0
	v_mul_f32_e32 v0, v50, v0
	v_cvt_pk_bf16_f32 v0, v0, s0
	ds_write_b16 v145, v0
	v_mul_f32_e32 v0, v55, v67
	v_mul_f32_e32 v50, v51, v67
	v_mul_f32_e32 v51, 0xbfb8aa3b, v0
	v_exp_f32_e32 v51, v51
	v_mfma_f32_16x16x32_bf16 v[14:17], v[90:93], v[102:105], v[82:85]
	v_add_f32_e32 v51, 1.0, v51
	v_div_scale_f32 v54, s[12:13], v51, v51, v0
	v_rcp_f32_e32 v55, v54
	v_mfma_f32_16x16x32_bf16 v[2:5], v[90:93], v[106:109], v[6:9]
	v_fma_f32 v58, -v54, v55, 1.0
	v_fmac_f32_e32 v55, v58, v55
	v_div_scale_f32 v58, vcc, v0, v51, v0
	v_mul_f32_e32 v59, v58, v55
	v_fma_f32 v62, -v54, v59, v58
; DI float siluf_(float x) { return x / (1.f + __expf(-x)); }
; template <int BN_OUT> DI void ct_put(bf16* lds, int row, int col, float v) { lds[row * (BN_OUT + 8) + col] = f2bf(v); }
; DI void phase_tail(const Ctx& c) {
;     ...
;       for (int i = 0; i < 4; ++i)
; #pragma unroll
;         for (int r = 0; r < 4; ++r) {
;           const int row = wm * 64 + i * 16 + (lane >> 4) * 4 + r;
;           const float rs = rstd2[row];
; #pragma unroll
;           for (int pp = 0; pp < 2; ++pp) {
;             const float g = acc[i][2 * pp][r] * rs, u = acc[i][2 * pp + 1][r] * rs;
;             ct_put<128>(lds, row, (wn * 2 + pp) * 16 + (lane & 15), siluf_(g) * u);
;           }
;         }
	v_fmac_f32_e32 v59, v62, v55
	v_fma_f32 v54, -v54, v59, v58
	v_div_fmas_f32 v54, v54, v55, v59
	v_div_fixup_f32 v0, v54, v51, v0
	v_mul_f32_e32 v0, v50, v0
	v_cvt_pk_bf16_f32 v0, v0, s0
	ds_write_b16 v145, v0 offset:32
	v_mul_f32_e32 v0, v64, v68
	v_mul_f32_e32 v51, 0xbfb8aa3b, v0
	v_exp_f32_e32 v51, v51
	v_mul_f32_e32 v50, v60, v68
	v_mfma_f32_16x16x32_bf16 v[6:9], v[90:93], v[110:113], v[78:81]
	v_add_f32_e32 v51, 1.0, v51
	v_div_scale_f32 v54, s[12:13], v51, v51, v0
	v_rcp_f32_e32 v55, v54
	s_nop 0
	v_fma_f32 v58, -v54, v55, 1.0
	v_fmac_f32_e32 v55, v58, v55
	v_div_scale_f32 v58, vcc, v0, v51, v0
	v_mul_f32_e32 v59, v58, v55
	v_fma_f32 v60, -v54, v59, v58
	v_fmac_f32_e32 v59, v60, v55
	v_fma_f32 v54, -v54, v59, v58
	v_div_fmas_f32 v54, v54, v55, v59
	v_div_fixup_f32 v0, v54, v51, v0
	v_mul_f32_e32 v0, v50, v0
	v_cvt_pk_bf16_f32 v0, v0, s0
	ds_write_b16 v146, v0
	v_mul_f32_e32 v0, v56, v68
	v_mul_f32_e32 v51, 0xbfb8aa3b, v0
	v_exp_f32_e32 v51, v51
	v_mul_f32_e32 v50, v52, v68
	v_add_f32_e32 v51, 1.0, v51
	v_min_f32_e32 v51, 0x7f7fffff, v51
	v_rcp_f32_e32 v230, v51
	s_nop 0
	v_fma_f32 v231, -v51, v230, 1.0
	v_fma_f32 v230, v231, v230, v230
	v_mul_f32_e32 v0, v0, v230
	v_mul_f32_e32 v0, v50, v0
	v_cvt_pk_bf16_f32 v0, v0, s0
	ds_write_b16 v146, v0 offset:32
	v_mul_f32_e32 v0, v65, v69
	v_mul_f32_e32 v51, 0xbfb8aa3b, v0
	v_exp_f32_e32 v51, v51
	v_mul_f32_e32 v50, v61, v69
	v_add_f32_e32 v51, 1.0, v51
	v_min_f32_e32 v51, 0x7f7fffff, v51
	v_rcp_f32_e32 v230, v51
	s_nop 0
	v_fma_f32 v231, -v51, v230, 1.0
	v_fma_f32 v230, v231, v230, v230
	v_mul_f32_e32 v0, v0, v230
	v_mul_f32_e32 v0, v50, v0
	v_cvt_pk_bf16_f32 v0, v0, s0
	ds_write_b16 v147, v0
	v_mul_f32_e32 v0, v57, v69
	v_mul_f32_e32 v51, 0xbfb8aa3b, v0
	v_exp_f32_e32 v51, v51
	v_mul_f32_e32 v50, v53, v69
	v_add_f32_e32 v51, 1.0, v51
	v_min_f32_e32 v51, 0x7f7fffff, v51
	v_rcp_f32_e32 v230, v51
	s_nop 0
	v_fma_f32 v231, -v51, v230, 1.0
	v_fma_f32 v230, v231, v230, v230
	v_mul_f32_e32 v0, v0, v230
	v_mul_f32_e32 v0, v50, v0
	ds_read_b128 v[50:53], v148
	v_cvt_pk_bf16_f32 v0, v0, s0
	ds_write_b16 v147, v0 offset:32
	s_waitcnt lgkmcnt(1)
	v_mul_f32_e32 v0, v42, v50
	v_mul_f32_e32 v42, v46, v50
	v_mul_f32_e32 v46, 0xbfb8aa3b, v0
	v_exp_f32_e32 v46, v46
	s_nop 0
	v_add_f32_e32 v46, 1.0, v46
	v_min_f32_e32 v46, 0x7f7fffff, v46
	v_rcp_f32_e32 v230, v46
	s_nop 0
	v_fma_f32 v231, -v46, v230, 1.0
	v_fma_f32 v230, v231, v230, v230
	v_mul_f32_e32 v0, v0, v230
	v_mul_f32_e32 v0, v42, v0
	v_cvt_pk_bf16_f32 v0, v0, s0
	ds_write_b16 v149, v0
	v_mul_f32_e32 v0, v34, v50
	v_mul_f32_e32 v34, v38, v50
	v_mul_f32_e32 v38, 0xbfb8aa3b, v0
	v_exp_f32_e32 v38, v38
	s_nop 0
	v_add_f32_e32 v38, 1.0, v38
	v_min_f32_e32 v38, 0x7f7fffff, v38
	v_rcp_f32_e32 v230, v38
	s_nop 0
	v_fma_f32 v231, -v38, v230, 1.0
	v_fma_f32 v230, v231, v230, v230
	v_mul_f32_e32 v0, v0, v230
	v_mul_f32_e32 v0, v34, v0
	v_cvt_pk_bf16_f32 v0, v0, s0
	ds_write_b16 v149, v0 offset:32
	v_mul_f32_e32 v0, v43, v51
	v_mul_f32_e32 v38, 0xbfb8aa3b, v0
	v_exp_f32_e32 v38, v38
	v_mul_f32_e32 v34, v47, v51
	v_add_f32_e32 v38, 1.0, v38
	v_min_f32_e32 v38, 0x7f7fffff, v38
	v_rcp_f32_e32 v230, v38
	s_nop 0
	v_fma_f32 v231, -v38, v230, 1.0
	v_fma_f32 v230, v231, v230, v230
	v_mul_f32_e32 v0, v0, v230
	v_mul_f32_e32 v0, v34, v0
	v_cvt_pk_bf16_f32 v0, v0, s0
	ds_write_b16 v150, v0
	v_mul_f32_e32 v0, v35, v51
	v_mul_f32_e32 v35, 0xbfb8aa3b, v0
	v_exp_f32_e32 v35, v35
	v_mul_f32_e32 v34, v39, v51
	v_add_f32_e32 v35, 1.0, v35
	v_min_f32_e32 v35, 0x7f7fffff, v35
	v_rcp_f32_e32 v230, v35
	s_nop 0
	v_fma_f32 v231, -v35, v230, 1.0
	v_fma_f32 v230, v231, v230, v230
	v_mul_f32_e32 v0, v0, v230
	v_mul_f32_e32 v0, v34, v0
	v_cvt_pk_bf16_f32 v0, v0, s0
	ds_write_b16 v150, v0 offset:32
	v_mul_f32_e32 v0, v44, v52
	v_mul_f32_e32 v35, 0xbfb8aa3b, v0
	v_exp_f32_e32 v35, v35
	v_mul_f32_e32 v34, v48, v52
	v_add_f32_e32 v35, 1.0, v35
	v_min_f32_e32 v35, 0x7f7fffff, v35
	v_rcp_f32_e32 v230, v35
	s_nop 0
	v_fma_f32 v231, -v35, v230, 1.0
	v_fma_f32 v230, v231, v230, v230
	v_mul_f32_e32 v0, v0, v230
	v_mul_f32_e32 v0, v34, v0
	v_cvt_pk_bf16_f32 v0, v0, s0
	ds_write_b16 v151, v0
	v_mul_f32_e32 v0, v36, v52
	v_mul_f32_e32 v35, 0xbfb8aa3b, v0
	v_exp_f32_e32 v35, v35
	v_mul_f32_e32 v34, v40, v52
	v_add_f32_e32 v35, 1.0, v35
	v_min_f32_e32 v35, 0x7f7fffff, v35
	v_rcp_f32_e32 v230, v35
	s_nop 0
	v_fma_f32 v231, -v35, v230, 1.0
	v_fma_f32 v230, v231, v230, v230
	v_mul_f32_e32 v0, v0, v230
	v_mul_f32_e32 v0, v34, v0
	v_cvt_pk_bf16_f32 v0, v0, s0
	ds_write_b16 v151, v0 offset:32
	v_mul_f32_e32 v0, v45, v53
	v_mul_f32_e32 v35, 0xbfb8aa3b, v0
	v_exp_f32_e32 v35, v35
	v_mul_f32_e32 v34, v49, v53
	v_add_f32_e32 v35, 1.0, v35
	v_min_f32_e32 v35, 0x7f7fffff, v35
	v_rcp_f32_e32 v230, v35
	s_nop 0
	v_fma_f32 v231, -v35, v230, 1.0
	v_fma_f32 v230, v231, v230, v230
	v_mul_f32_e32 v0, v0, v230
	v_mul_f32_e32 v0, v34, v0
	v_cvt_pk_bf16_f32 v0, v0, s0
	ds_write_b16 v152, v0
	v_mul_f32_e32 v0, v37, v53
	v_mul_f32_e32 v35, 0xbfb8aa3b, v0
	v_exp_f32_e32 v35, v35
	v_mul_f32_e32 v34, v41, v53
	v_add_f32_e32 v35, 1.0, v35
	v_min_f32_e32 v35, 0x7f7fffff, v35
	v_rcp_f32_e32 v230, v35
	s_nop 0
	v_fma_f32 v231, -v35, v230, 1.0
	v_fma_f32 v230, v231, v230, v230
	v_mul_f32_e32 v0, v0, v230
	v_mul_f32_e32 v0, v34, v0
	ds_read_b128 v[34:37], v153
	v_cvt_pk_bf16_f32 v0, v0, s0
	ds_write_b16 v152, v0 offset:32
	s_waitcnt lgkmcnt(1)
; DI int otid() { int t = (int)__builtin_amdgcn_workitem_id_x(); asm volatile("" : "+v"(t)); return t; }
; DI float siluf_(float x) { return x / (1.f + __expf(-x)); }
; template <int BN_OUT> DI void ct_put(bf16* lds, int row, int col, float v) { lds[row * (BN_OUT + 8) + col] = f2bf(v); }
; template <int BM, int BN_OUT>
; DI void ct_flush(bf16* lds, bf16* dst, int ldd) {
;   __syncthreads();
;   constexpr int CH = BN_OUT / 8;
;   for (int id = otid(); id < BM * CH; id += NTHR) {
;     const int row = id / CH, ch = id - row * CH;
;     *(u32x4*)(dst + (size_t)row * ldd + ch * 8) = *(const u32x4*)(lds + row * (BN_OUT + 8) + ch * 8);
; DI void phase_tail(const Ctx& c) {
;     ...
;       for (int i = 0; i < 4; ++i)
; #pragma unroll
;         for (int r = 0; r < 4; ++r) {
;           const int row = wm * 64 + i * 16 + (lane >> 4) * 4 + r;
;           const float rs = rstd2[row];
; #pragma unroll
;           for (int pp = 0; pp < 2; ++pp) {
;             const float g = acc[i][2 * pp][r] * rs, u = acc[i][2 * pp + 1][r] * rs;
;             ct_put<128>(lds, row, (wn * 2 + pp) * 16 + (lane & 15), siluf_(g) * u);
;           }
;         }
;       ct_flush<128, 128>(lds, F + (size_t)m0 * DFF + nt * 128, DFF);
	v_mul_f32_e32 v0, v26, v34
	v_mul_f32_e32 v26, v30, v34
	v_mul_f32_e32 v30, 0xbfb8aa3b, v0
	v_exp_f32_e32 v30, v30
	s_nop 0
	v_add_f32_e32 v30, 1.0, v30
	v_min_f32_e32 v30, 0x7f7fffff, v30
	v_rcp_f32_e32 v230, v30
	s_nop 0
	v_fma_f32 v231, -v30, v230, 1.0
	v_fma_f32 v230, v231, v230, v230
	v_mul_f32_e32 v0, v0, v230
	v_mul_f32_e32 v0, v26, v0
	v_cvt_pk_bf16_f32 v0, v0, s0
	ds_write_b16 v154, v0
	v_mul_f32_e32 v0, v18, v34
	v_mul_f32_e32 v18, v22, v34
	v_mul_f32_e32 v22, 0xbfb8aa3b, v0
	v_exp_f32_e32 v22, v22
	s_nop 0
	v_add_f32_e32 v22, 1.0, v22
	v_min_f32_e32 v22, 0x7f7fffff, v22
	v_rcp_f32_e32 v230, v22
	s_nop 0
	v_fma_f32 v231, -v22, v230, 1.0
	v_fma_f32 v230, v231, v230, v230
	v_mul_f32_e32 v0, v0, v230
	v_mul_f32_e32 v0, v18, v0
	v_cvt_pk_bf16_f32 v0, v0, s0
	ds_write_b16 v154, v0 offset:32
	v_mul_f32_e32 v0, v27, v35
	v_mul_f32_e32 v22, 0xbfb8aa3b, v0
	v_exp_f32_e32 v22, v22
	v_mul_f32_e32 v18, v31, v35
	v_add_f32_e32 v22, 1.0, v22
	v_min_f32_e32 v22, 0x7f7fffff, v22
	v_rcp_f32_e32 v230, v22
	s_nop 0
	v_fma_f32 v231, -v22, v230, 1.0
	v_fma_f32 v230, v231, v230, v230
	v_mul_f32_e32 v0, v0, v230
	v_mul_f32_e32 v0, v18, v0
	v_cvt_pk_bf16_f32 v0, v0, s0
	ds_write_b16 v155, v0
	v_mul_f32_e32 v0, v19, v35
	v_mul_f32_e32 v19, 0xbfb8aa3b, v0
	v_exp_f32_e32 v19, v19
	v_mul_f32_e32 v18, v23, v35
	v_add_f32_e32 v19, 1.0, v19
	v_min_f32_e32 v19, 0x7f7fffff, v19
	v_rcp_f32_e32 v230, v19
	s_nop 0
	v_fma_f32 v231, -v19, v230, 1.0
	v_fma_f32 v230, v231, v230, v230
	v_mul_f32_e32 v0, v0, v230
	v_mul_f32_e32 v0, v18, v0
	v_cvt_pk_bf16_f32 v0, v0, s0
	ds_write_b16 v155, v0 offset:32
	v_mul_f32_e32 v0, v28, v36
	v_mul_f32_e32 v19, 0xbfb8aa3b, v0
	v_exp_f32_e32 v19, v19
	v_mul_f32_e32 v18, v32, v36
	v_add_f32_e32 v19, 1.0, v19
	v_min_f32_e32 v19, 0x7f7fffff, v19
	v_rcp_f32_e32 v230, v19
	s_nop 0
	v_fma_f32 v231, -v19, v230, 1.0
	v_fma_f32 v230, v231, v230, v230
	v_mul_f32_e32 v0, v0, v230
	v_mul_f32_e32 v0, v18, v0
	v_cvt_pk_bf16_f32 v0, v0, s0
	ds_write_b16 v156, v0
	v_mul_f32_e32 v0, v20, v36
	v_mul_f32_e32 v19, 0xbfb8aa3b, v0
	v_exp_f32_e32 v19, v19
	v_mul_f32_e32 v18, v24, v36
	v_add_f32_e32 v19, 1.0, v19
	v_min_f32_e32 v19, 0x7f7fffff, v19
	v_rcp_f32_e32 v230, v19
	s_nop 0
	v_fma_f32 v231, -v19, v230, 1.0
	v_fma_f32 v230, v231, v230, v230
	v_mul_f32_e32 v0, v0, v230
	v_mul_f32_e32 v0, v18, v0
	v_cvt_pk_bf16_f32 v0, v0, s0
	ds_write_b16 v156, v0 offset:32
	v_mul_f32_e32 v0, v29, v37
	v_mul_f32_e32 v19, 0xbfb8aa3b, v0
	v_exp_f32_e32 v19, v19
	v_mul_f32_e32 v18, v33, v37
	v_add_f32_e32 v19, 1.0, v19
	v_min_f32_e32 v19, 0x7f7fffff, v19
	v_rcp_f32_e32 v230, v19
	s_nop 0
	v_fma_f32 v231, -v19, v230, 1.0
	v_fma_f32 v230, v231, v230, v230
	v_mul_f32_e32 v0, v0, v230
	v_mul_f32_e32 v0, v18, v0
	v_cvt_pk_bf16_f32 v0, v0, s0
	ds_write_b16 v157, v0
	v_mul_f32_e32 v0, v21, v37
	v_mul_f32_e32 v19, 0xbfb8aa3b, v0
	v_exp_f32_e32 v19, v19
	v_mul_f32_e32 v18, v25, v37
	v_add_f32_e32 v19, 1.0, v19
	v_min_f32_e32 v19, 0x7f7fffff, v19
	v_rcp_f32_e32 v230, v19
	s_nop 0
	v_fma_f32 v231, -v19, v230, 1.0
	v_fma_f32 v230, v231, v230, v230
	v_mul_f32_e32 v0, v0, v230
	v_mul_f32_e32 v0, v18, v0
	ds_read_b128 v[18:21], v158
	v_cvt_pk_bf16_f32 v0, v0, s0
	ds_write_b16 v157, v0 offset:32
	s_waitcnt lgkmcnt(1)
	v_mul_f32_e32 v0, v10, v18
	v_mul_f32_e32 v10, v14, v18
	v_mul_f32_e32 v14, 0xbfb8aa3b, v0
	v_exp_f32_e32 v14, v14
	s_nop 0
	v_add_f32_e32 v14, 1.0, v14
	v_min_f32_e32 v14, 0x7f7fffff, v14
	v_rcp_f32_e32 v230, v14
	s_nop 0
	v_fma_f32 v231, -v14, v230, 1.0
	v_fma_f32 v230, v231, v230, v230
	v_mul_f32_e32 v0, v0, v230
	v_mul_f32_e32 v0, v10, v0
	v_cvt_pk_bf16_f32 v0, v0, s0
	ds_write_b16 v159, v0
	v_mul_f32_e32 v0, v2, v18
	v_mul_f32_e32 v2, v6, v18
	v_mul_f32_e32 v6, 0xbfb8aa3b, v0
	v_exp_f32_e32 v6, v6
	s_nop 0
	v_add_f32_e32 v6, 1.0, v6
	v_min_f32_e32 v6, 0x7f7fffff, v6
	v_rcp_f32_e32 v230, v6
	s_nop 0
	v_fma_f32 v231, -v6, v230, 1.0
	v_fma_f32 v230, v231, v230, v230
	v_mul_f32_e32 v0, v0, v230
	v_mul_f32_e32 v0, v2, v0
	v_cvt_pk_bf16_f32 v0, v0, s0
	ds_write_b16 v159, v0 offset:32
	v_mul_f32_e32 v0, v11, v19
	v_mul_f32_e32 v6, 0xbfb8aa3b, v0
	v_exp_f32_e32 v6, v6
	v_mul_f32_e32 v2, v15, v19
	v_add_f32_e32 v6, 1.0, v6
	v_min_f32_e32 v6, 0x7f7fffff, v6
	v_rcp_f32_e32 v230, v6
	s_nop 0
	v_fma_f32 v231, -v6, v230, 1.0
	v_fma_f32 v230, v231, v230, v230
	v_mul_f32_e32 v0, v0, v230
	v_mul_f32_e32 v0, v2, v0
	v_cvt_pk_bf16_f32 v0, v0, s0
	ds_write_b16 v160, v0
	v_mul_f32_e32 v0, v3, v19
	v_mul_f32_e32 v3, 0xbfb8aa3b, v0
	v_exp_f32_e32 v3, v3
	v_mul_f32_e32 v2, v7, v19
	v_add_f32_e32 v3, 1.0, v3
	v_min_f32_e32 v3, 0x7f7fffff, v3
	v_rcp_f32_e32 v230, v3
	s_nop 0
	v_fma_f32 v231, -v3, v230, 1.0
	v_fma_f32 v230, v231, v230, v230
	v_mul_f32_e32 v0, v0, v230
	v_mul_f32_e32 v0, v2, v0
	v_cvt_pk_bf16_f32 v0, v0, s0
	ds_write_b16 v160, v0 offset:32
	v_mul_f32_e32 v0, v12, v20
	v_mul_f32_e32 v3, 0xbfb8aa3b, v0
	v_exp_f32_e32 v3, v3
	v_mul_f32_e32 v2, v16, v20
	v_add_f32_e32 v3, 1.0, v3
	v_min_f32_e32 v3, 0x7f7fffff, v3
	v_rcp_f32_e32 v230, v3
	s_nop 0
	v_fma_f32 v231, -v3, v230, 1.0
	v_fma_f32 v230, v231, v230, v230
	v_mul_f32_e32 v0, v0, v230
	v_mul_f32_e32 v0, v2, v0
	v_cvt_pk_bf16_f32 v0, v0, s0
	ds_write_b16 v161, v0
	v_mul_f32_e32 v0, v4, v20
	v_mul_f32_e32 v3, 0xbfb8aa3b, v0
	v_exp_f32_e32 v3, v3
	v_mul_f32_e32 v2, v8, v20
	v_add_f32_e32 v3, 1.0, v3
	v_min_f32_e32 v3, 0x7f7fffff, v3
	v_rcp_f32_e32 v230, v3
	s_nop 0
	v_fma_f32 v231, -v3, v230, 1.0
	v_fma_f32 v230, v231, v230, v230
	v_mul_f32_e32 v0, v0, v230
	v_mul_f32_e32 v0, v2, v0
	v_cvt_pk_bf16_f32 v0, v0, s0
	ds_write_b16 v161, v0 offset:32
	v_mul_f32_e32 v0, v13, v21
	v_mul_f32_e32 v3, 0xbfb8aa3b, v0
	v_exp_f32_e32 v3, v3
	v_mul_f32_e32 v2, v17, v21
	v_add_f32_e32 v3, 1.0, v3
	v_min_f32_e32 v3, 0x7f7fffff, v3
	v_rcp_f32_e32 v230, v3
	s_nop 0
	v_fma_f32 v231, -v3, v230, 1.0
	v_fma_f32 v230, v231, v230, v230
	v_mul_f32_e32 v0, v0, v230
	v_mul_f32_e32 v0, v2, v0
	v_cvt_pk_bf16_f32 v0, v0, s0
	ds_write_b16 v162, v0
	v_mul_f32_e32 v0, v5, v21
	v_mul_f32_e32 v3, 0xbfb8aa3b, v0
	v_exp_f32_e32 v3, v3
	v_mul_f32_e32 v2, v9, v21
	v_add_f32_e32 v3, 1.0, v3
	v_min_f32_e32 v3, 0x7f7fffff, v3
	v_rcp_f32_e32 v230, v3
	s_nop 0
	v_fma_f32 v231, -v3, v230, 1.0
	v_fma_f32 v230, v231, v230, v230
	v_mul_f32_e32 v0, v0, v230
	v_mul_f32_e32 v0, v2, v0
	v_cvt_pk_bf16_f32 v0, v0, s0
	ds_write_b16 v162, v0 offset:32
	v_mov_b32_e32 v0, v186
	s_waitcnt lgkmcnt(0)
	s_barrier
	s_nop 0
	v_cmp_gt_i32_e32 vcc, s11, v0
	s_and_saveexec_b64 s[28:29], vcc
	s_movk_i32 s14, 0x5ff
	s_movk_i32 s15, 0x1600
	s_cbranch_execz .LBB0_853
	s_lshl_b32 s11, s10, 8
	s_add_u32 s30, s24, s11
	s_addc_u32 s31, s25, 0
	v_lshl_add_u32 v2, v0, 4, v190
	v_lshlrev_b32_e32 v3, 3, v0
	s_mov_b64 s[34:35], 0
